# attention epilogue: the three epilogue barriers wait with vmcnt(4) (tile DMA + ticket) and leave the four gate loads in flight until the store pass
# baseline (speedup 1.0000x reference)
.LBB0_652:
	s_or_b64 exec, exec, s[14:15]
	s_add_i32 s14, 0, 0x18000
	s_waitcnt vmcnt(4) lgkmcnt(0)
	s_barrier
	v_add_u32_e32 v81, s14, v144
	v_add_u32_e32 v139, s14, v159
	v_add_u32_e32 v82, s14, v157
	ds_read_b128 v[96:99], v81
	ds_read_b128 v[100:103], v82
	v_add_u32_e32 v141, s14, v160
	ds_read_b128 v[104:107], v139
	ds_read_b128 v[108:111], v141
	v_or_b32_e32 v80, 0x4000, v166
	v_add_u32_e32 v142, v162, v80
	v_add_u32_e32 v140, v163, v80
	v_add_u32_e32 v138, v164, v80
	v_add_u32_e32 v137, v165, v80
	ds_read_b128 v[162:165], v81 offset:4096
	ds_read_b128 v[166:169], v82 offset:4096
	s_waitcnt lgkmcnt(5)
	v_mfma_f32_32x32x16_bf16 v[80:95], v[96:99], v[124:127], v[0:15]
	v_cvt_pk_bf16_f32 v128, v194, v195
	v_cvt_pk_bf16_f32 v129, v196, v197
	v_cvt_pk_bf16_f32 v130, v198, v200
	v_cvt_pk_bf16_f32 v131, v199, v201
	s_waitcnt lgkmcnt(4)
	v_mfma_f32_32x32x16_bf16 v[80:95], v[100:103], v[120:123], v[80:95]
	ds_read_b128 v[202:205], v139 offset:4096
	ds_read_b128 v[206:209], v141 offset:4096
	v_cvt_pk_bf16_f32 v132, v180, v181
	v_cvt_pk_bf16_f32 v133, v182, v183
	v_cvt_pk_bf16_f32 v134, v193, v189
	v_cvt_pk_bf16_f32 v135, v190, v192
	s_waitcnt lgkmcnt(5)
	v_mfma_f32_32x32x16_bf16 v[80:95], v[104:107], v[116:119], v[80:95]
	s_add_i32 s15, 0, 0x10000
	v_add_u32_e32 v139, s15, v142
	v_add_u32_e32 v141, s15, v140
	ds_read_b128 v[214:217], v139
	ds_read_b128 v[218:221], v141
	v_cvt_pk_bf16_f32 v210, v173, v174
	v_cvt_pk_bf16_f32 v211, v175, v176
	v_cvt_pk_bf16_f32 v212, v191, v188
	v_cvt_pk_bf16_f32 v213, v171, v172
	s_waitcnt lgkmcnt(6)
	v_mfma_f32_32x32x16_bf16 v[80:95], v[108:111], v[112:115], v[80:95]
	v_add_u32_e32 v143, s15, v138
	v_add_u32_e32 v144, s15, v137
	ds_read_b128 v[226:229], v143
	ds_read_b128 v[230:233], v144
	v_cvt_pk_bf16_f32 v222, v185, v186
	v_cvt_pk_bf16_f32 v223, v187, v184
	v_cvt_pk_bf16_f32 v224, v177, v178
	v_cvt_pk_bf16_f32 v225, v179, v161
	v_add_f32_e32 v96, 0, v194
	v_add_f32_e32 v96, v195, v96
	v_add_f32_e32 v96, v196, v96
	v_add_f32_e32 v96, v197, v96
	v_add_f32_e32 v96, v198, v96
	v_add_f32_e32 v157, v200, v96
	s_waitcnt lgkmcnt(7)
	v_mfma_f32_32x32x16_bf16 v[96:111], v[162:165], v[124:127], v[0:15]
	v_add_f32_e32 v124, v199, v157
	v_add_f32_e32 v124, v201, v124
	s_waitcnt lgkmcnt(6)
	v_mfma_f32_32x32x16_bf16 v[96:111], v[166:169], v[120:123], v[96:111]
	v_exp_f32_e32 v125, v80
	v_exp_f32_e32 v126, v81
	v_exp_f32_e32 v127, v82
	v_exp_f32_e32 v157, v83
	s_waitcnt lgkmcnt(5)
	v_mfma_f32_32x32x16_bf16 v[96:111], v[202:205], v[116:119], v[96:111]
	v_exp_f32_e32 v122, v84
	v_exp_f32_e32 v123, v85
	v_exp_f32_e32 v159, v86
	v_exp_f32_e32 v160, v87
	s_waitcnt lgkmcnt(4)
	v_mfma_f32_32x32x16_bf16 v[96:111], v[206:209], v[112:115], v[96:111]
	v_exp_f32_e32 v162, v88
	v_exp_f32_e32 v163, v89
	v_exp_f32_e32 v164, v90
	v_exp_f32_e32 v165, v91
	s_waitcnt lgkmcnt(3)
	v_mfma_f32_32x32x16_bf16 v[64:79], v[128:131], v[214:217], v[64:79]
	ds_read_b128 v[80:83], v139 offset:4096
	v_exp_f32_e32 v166, v92
	v_exp_f32_e32 v167, v93
	v_exp_f32_e32 v168, v94
	v_exp_f32_e32 v169, v95
	s_waitcnt lgkmcnt(3)
	v_mfma_f32_32x32x16_bf16 v[64:79], v[132:135], v[218:221], v[64:79]
	v_add_f32_e32 v88, v180, v124
	v_add_f32_e32 v88, v181, v88
	ds_read_b128 v[84:87], v141 offset:4096
	v_add_f32_e32 v88, v182, v88
	v_add_f32_e32 v88, v183, v88
	v_add_f32_e32 v88, v193, v88
	v_add_f32_e32 v88, v189, v88
	v_add_f32_e32 v88, v190, v88
	v_add_f32_e32 v112, v192, v88
	s_waitcnt lgkmcnt(3)
	v_mfma_f32_32x32x16_bf16 v[64:79], v[210:213], v[226:229], v[64:79]
	ds_read_b128 v[88:91], v143 offset:4096
	v_exp_f32_e32 v124, v96
	v_exp_f32_e32 v170, v97
	v_exp_f32_e32 v180, v98
	v_exp_f32_e32 v181, v99
	s_waitcnt lgkmcnt(3)
	v_mfma_f32_32x32x16_bf16 v[64:79], v[222:225], v[230:233], v[64:79]
	ds_read_b128 v[92:95], v144 offset:4096
	v_add_f32_e32 v96, v173, v112
	v_add_f32_e32 v96, v174, v96
	v_add_f32_e32 v96, v175, v96
	v_add_f32_e32 v96, v176, v96
	v_add_f32_e32 v96, v191, v96
	v_add_f32_e32 v112, v188, v96
	s_waitcnt lgkmcnt(3)
	v_mfma_f32_32x32x16_bf16 v[48:63], v[128:131], v[80:83], v[48:63]
	ds_read_b128 v[96:99], v139 offset:8192
	v_exp_f32_e32 v173, v100
	v_exp_f32_e32 v174, v101
	v_exp_f32_e32 v175, v102
	v_exp_f32_e32 v176, v103
	s_waitcnt lgkmcnt(3)
	v_mfma_f32_32x32x16_bf16 v[48:63], v[132:135], v[84:87], v[48:63]
	ds_read_b128 v[80:83], v141 offset:8192
	v_add_f32_e32 v100, v171, v112
	v_add_f32_e32 v100, v172, v100
	v_add_f32_e32 v100, v185, v100
	v_add_f32_e32 v100, v186, v100
	v_add_f32_e32 v100, v187, v100
	v_add_f32_e32 v100, v184, v100
	s_waitcnt lgkmcnt(3)
	v_mfma_f32_32x32x16_bf16 v[48:63], v[210:213], v[88:91], v[48:63]
	ds_read_b128 v[84:87], v143 offset:8192
	v_exp_f32_e32 v171, v104
	v_exp_f32_e32 v172, v105
	v_exp_f32_e32 v182, v106
	v_exp_f32_e32 v183, v107
	s_waitcnt lgkmcnt(3)
	v_mfma_f32_32x32x16_bf16 v[48:63], v[222:225], v[92:95], v[48:63]
	ds_read_b128 v[88:91], v144 offset:8192
	v_add_f32_e32 v100, v177, v100
	v_add_f32_e32 v100, v178, v100
	v_add_f32_e32 v177, v179, v100
	s_waitcnt lgkmcnt(3)
	v_mfma_f32_32x32x16_bf16 v[32:47], v[128:131], v[96:99], v[32:47]
	ds_read_b128 v[92:95], v139 offset:12288
	v_exp_f32_e32 v178, v108
	v_exp_f32_e32 v179, v109
	v_exp_f32_e32 v184, v110
	v_exp_f32_e32 v185, v111
	s_waitcnt lgkmcnt(3)
	v_mfma_f32_32x32x16_bf16 v[32:47], v[132:135], v[80:83], v[32:47]
	ds_read_b128 v[96:99], v141 offset:12288
	s_waitcnt lgkmcnt(3)
	v_mfma_f32_32x32x16_bf16 v[32:47], v[210:213], v[84:87], v[32:47]
	ds_read_b128 v[80:83], v143 offset:12288
	s_waitcnt lgkmcnt(3)
	v_mfma_f32_32x32x16_bf16 v[32:47], v[222:225], v[88:91], v[32:47]
	ds_read_b128 v[84:87], v144 offset:12288
	s_waitcnt lgkmcnt(3)
	v_mfma_f32_32x32x16_bf16 v[16:31], v[128:131], v[92:95], v[16:31]
	s_add_u32 s12, s12, 0x230000
	s_addc_u32 s13, s13, 0
	s_mov_b32 s15, m0
	s_mov_b32 m0, s71
	s_nop 0
	global_load_lds_dwordx4 v156, s[12:13]
	s_mov_b32 m0, s15
	s_waitcnt lgkmcnt(2)
	v_mfma_f32_32x32x16_bf16 v[16:31], v[132:135], v[96:99], v[16:31]
	s_mov_b32 s15, m0
	s_mov_b32 m0, s72
	s_nop 0
	global_load_lds_dwordx4 v154, s[12:13]
	s_mov_b32 m0, s15
	s_waitcnt lgkmcnt(1)
	v_mfma_f32_32x32x16_bf16 v[16:31], v[210:213], v[80:83], v[16:31]
	s_add_u32 s10, s10, 0x1180
	s_addc_u32 s11, s11, 0
	s_mov_b32 s12, m0
	s_mov_b32 m0, s73
	s_nop 0
	global_load_lds_dwordx4 v150, s[10:11]
	s_mov_b32 m0, s12
	s_waitcnt lgkmcnt(0)
	v_mfma_f32_32x32x16_bf16 v[16:31], v[222:225], v[84:87], v[16:31]
	s_mov_b32 s12, m0
	s_mov_b32 m0, s78
	s_nop 0
	global_load_lds_dwordx4 v148, s[10:11]
	s_mov_b32 m0, s12
	v_add_u32_e32 v80, s14, v142
	v_cvt_pk_bf16_f32 v98, v125, v126
	v_cvt_pk_bf16_f32 v99, v127, v157
	v_cvt_pk_bf16_f32 v100, v122, v123
	v_cvt_pk_bf16_f32 v101, v159, v160
	ds_read_b128 v[80:83], v80
	v_add_u32_e32 v84, s14, v140
	ds_read_b128 v[84:87], v84
	s_waitcnt lgkmcnt(1)
	v_mfma_f32_32x32x16_bf16 v[64:79], v[98:101], v[80:83], v[64:79]
	v_cvt_pk_bf16_f32 v102, v162, v163
	v_cvt_pk_bf16_f32 v103, v164, v165
	v_cvt_pk_bf16_f32 v104, v166, v167
	v_cvt_pk_bf16_f32 v105, v168, v169
	v_add_u32_e32 v80, s14, v138
	v_cvt_pk_bf16_f32 v106, v124, v170
	v_cvt_pk_bf16_f32 v107, v180, v181
	s_waitcnt lgkmcnt(0)
	v_mfma_f32_32x32x16_bf16 v[64:79], v[102:105], v[84:87], v[64:79]
	v_cvt_pk_bf16_f32 v108, v173, v174
	v_cvt_pk_bf16_f32 v109, v175, v176
	ds_read_b128 v[80:83], v80
	v_add_u32_e32 v84, s14, v137
	ds_read_b128 v[84:87], v84
	v_cvt_pk_bf16_f32 v110, v171, v172
	v_cvt_pk_bf16_f32 v111, v182, v183
	s_waitcnt lgkmcnt(1)
	v_mfma_f32_32x32x16_bf16 v[64:79], v[106:109], v[80:83], v[64:79]
	v_cvt_pk_bf16_f32 v112, v178, v179
	v_cvt_pk_bf16_f32 v113, v184, v185
	v_add_u32_e32 v80, s91, v142
	ds_read_b128 v[80:83], v80
	v_ashrrev_i32_e32 v88, 4, v146
	v_add_u32_e32 v139, s69, v88
	s_lshl_b32 s10, s60, 1
	s_waitcnt lgkmcnt(1)
	v_mfma_f32_32x32x16_bf16 v[64:79], v[110:113], v[84:87], v[64:79]
	v_add_u32_e32 v84, s91, v140
	ds_read_b128 v[84:87], v84
	v_add_u32_e32 v96, s59, v139
	s_add_u32 s4, s4, s10
	s_addc_u32 s5, s5, 0
	v_ashrrev_i32_e32 v97, 31, v96
	v_add_u32_e32 v118, s92, v140
	s_waitcnt lgkmcnt(1)
	v_mfma_f32_32x32x16_bf16 v[48:63], v[98:101], v[80:83], v[48:63]
	v_lshlrev_b32_e32 v80, 3, v146
	v_and_b32_e32 v143, 0x78, v80
	v_add_u32_e32 v80, s91, v138
	ds_read_b128 v[80:83], v80
	v_lshlrev_b32_e32 v144, 1, v143
	v_lshl_add_u64 v[88:89], s[4:5], 0, v[144:145]
	s_mov_b32 s4, 0x9c01000
	s_waitcnt lgkmcnt(1)
	v_mfma_f32_32x32x16_bf16 v[48:63], v[102:105], v[84:87], v[48:63]
	v_lshlrev_b64 v[84:85], 10, v[96:97]
	v_lshl_add_u64 v[114:115], v[88:89], 0, v[84:85]
	v_add_u32_e32 v84, s91, v137
	ds_read_b128 v[84:87], v84
	v_add_f32_e32 v125, 0, v125
	s_waitcnt lgkmcnt(1)
	v_mfma_f32_32x32x16_bf16 v[48:63], v[106:109], v[80:83], v[48:63]
	v_add_co_u32_e64 v80, s[4:5], s4, v114
	s_nop 1
	v_addc_co_u32_e64 v81, s[4:5], 0, v115, s[4:5]
	s_mov_b32 s4, 0x9c03000
	global_load_dwordx4 v[92:95], v[80:81], off offset:-4096
	global_load_dwordx4 v[88:91], v[80:81], off
	v_add_co_u32_e64 v80, s[4:5], s4, v114
	s_waitcnt lgkmcnt(0)
	v_mfma_f32_32x32x16_bf16 v[48:63], v[110:113], v[84:87], v[48:63]
	v_addc_co_u32_e64 v81, s[4:5], 0, v115, s[4:5]
	global_load_dwordx4 v[84:87], v[80:81], off offset:-4096
	s_nop 0
	global_load_dwordx4 v[80:83], v[80:81], off
	v_add_u32_e32 v114, s92, v142
	ds_read_b128 v[114:117], v114
	ds_read_b128 v[118:121], v118
	s_waitcnt lgkmcnt(1)
	v_mfma_f32_32x32x16_bf16 v[32:47], v[98:101], v[114:117], v[32:47]
	v_add_f32_e32 v114, 0, v124
	v_add_f32_e32 v115, v126, v125
	v_add_f32_e32 v114, v170, v114
	v_add_f32_e32 v115, v127, v115
	v_add_f32_e32 v114, v180, v114
	v_add_f32_e32 v115, v157, v115
	v_add_f32_e32 v124, v181, v114
	s_waitcnt lgkmcnt(0)
	v_mfma_f32_32x32x16_bf16 v[32:47], v[102:105], v[118:121], v[32:47]
	v_add_u32_e32 v114, s92, v138
	v_add_f32_e32 v118, v122, v115
	ds_read_b128 v[114:117], v114
	v_add_f32_e32 v123, v123, v118
	v_add_u32_e32 v118, s92, v137
	ds_read_b128 v[118:121], v118
	v_add_f32_e32 v122, v173, v124
	s_waitcnt lgkmcnt(1)
	v_mfma_f32_32x32x16_bf16 v[32:47], v[106:109], v[114:117], v[32:47]
	v_add_f32_e32 v114, v174, v122
	v_add_f32_e32 v115, v159, v123
	v_add_f32_e32 v114, v175, v114
	v_add_f32_e32 v115, v160, v115
	v_add_f32_e32 v114, v176, v114
	v_add_f32_e32 v115, v162, v115
	v_add_f32_e32 v122, v171, v114
	v_add_u32_e32 v114, s93, v142
	s_waitcnt lgkmcnt(0)
	v_mfma_f32_32x32x16_bf16 v[32:47], v[110:113], v[118:121], v[32:47]
	v_add_f32_e32 v118, v163, v115
	ds_read_b128 v[114:117], v114
	v_add_f32_e32 v123, v164, v118
	v_add_u32_e32 v118, s93, v140
	ds_read_b128 v[118:121], v118
	v_add_f32_e32 v122, v172, v122
	s_waitcnt lgkmcnt(1)
	v_mfma_f32_32x32x16_bf16 v[16:31], v[98:101], v[114:117], v[16:31]
	v_add_f32_e32 v98, v182, v122
	v_add_f32_e32 v99, v165, v123
	v_add_f32_e32 v98, v183, v98
	v_add_f32_e32 v99, v166, v99
	v_add_f32_e32 v98, v178, v98
	v_add_f32_e32 v99, v167, v99
	v_add_f32_e32 v114, v179, v98
	s_waitcnt lgkmcnt(0)
	v_mfma_f32_32x32x16_bf16 v[16:31], v[102:105], v[118:121], v[16:31]
	v_add_u32_e32 v98, s93, v138
	v_add_f32_e32 v102, v168, v99
	ds_read_b128 v[98:101], v98
	v_add_f32_e32 v115, v169, v102
	v_add_u32_e32 v102, s93, v137
	ds_read_b128 v[102:105], v102
	v_add_f32_e32 v114, v184, v114
	s_waitcnt lgkmcnt(1)
	v_mfma_f32_32x32x16_bf16 v[16:31], v[106:109], v[98:101], v[16:31]
	v_add_f32_e32 v98, v185, v114
	v_add_f32_e32 v99, v161, v177
	v_add_f32_e32 v98, v115, v98
	v_add_f32_e32 v99, v158, v99
	v_lshlrev_b32_e32 v115, 2, v146
	v_add_f32_e32 v98, v99, v98
	v_xor_b32_e32 v99, 0x80, v115
	s_waitcnt lgkmcnt(0)
	v_mfma_f32_32x32x16_bf16 v[16:31], v[110:113], v[102:105], v[16:31]
	ds_bpermute_b32 v99, v99, v98
	s_waitcnt vmcnt(4) lgkmcnt(0)
	s_barrier
	s_and_saveexec_b64 s[4:5], vcc
	s_cbranch_execz .LBB0_654
	v_mov_b32_e32 v100, s89
	ds_write_b32 v100, v136

.LBB0_658:
	s_waitcnt vmcnt(4) lgkmcnt(0)
	s_barrier
	s_andn2_b64 vcc, exec, s[46:47]
	s_cbranch_vccnz .LBB0_660
	v_add_u32_e32 v168, 0x400, v166
	v_add_u32_e32 v169, 0x1000, v166
	v_add_u32_e32 v170, 0x1400, v166
	v_add_u32_e32 v171, 0x2000, v166
	v_add_u32_e32 v172, 0x2400, v166
	v_add_u32_e32 v173, 0x3000, v166
	v_add_u32_e32 v174, 0x3400, v166
	ds_read2_b32 v[98:99], v166 offset1:32
	ds_read2_b32 v[100:101], v166 offset0:128 offset1:160
	ds_read2_b32 v[102:103], v168 offset1:32
	ds_read2_b32 v[104:105], v168 offset0:128 offset1:160
	ds_read2_b32 v[106:107], v169 offset1:32
	ds_read2_b32 v[108:109], v169 offset0:128 offset1:160
	ds_read2_b32 v[110:111], v170 offset1:32
	ds_read2_b32 v[116:117], v170 offset0:128 offset1:160
	ds_read2_b32 v[118:119], v171 offset1:32
	ds_read2_b32 v[176:177], v171 offset0:128 offset1:160
	ds_read2_b32 v[178:179], v172 offset1:32
	ds_read2_b32 v[180:181], v172 offset0:128 offset1:160
	ds_read2_b32 v[182:183], v173 offset1:32
	ds_read2_b32 v[184:185], v173 offset0:128 offset1:160
	ds_read2_b32 v[186:187], v174 offset1:32
	ds_read2_b32 v[188:189], v174 offset0:128 offset1:160
	v_mov_b32_e32 v124, v64
	v_mov_b32_e32 v125, v48
	v_mov_b32_e32 v48, v65
	v_mov_b32_e32 v64, v66
	v_mov_b32_e32 v65, v50
	v_mov_b32_e32 v50, v67
	v_mov_b32_e32 v66, v68
	v_mov_b32_e32 v67, v52
	v_mov_b32_e32 v52, v69
	v_mov_b32_e32 v68, v70
	v_mov_b32_e32 v69, v54
	v_mov_b32_e32 v54, v71
	v_mov_b32_e32 v70, v72
	v_mov_b32_e32 v71, v56
	v_mov_b32_e32 v56, v73
	v_mov_b32_e32 v72, v74
	v_mov_b32_e32 v73, v58
	v_mov_b32_e32 v58, v75
	v_mov_b32_e32 v74, v76
	v_mov_b32_e32 v75, v60
	v_mov_b32_e32 v60, v77
	v_mov_b32_e32 v76, v78
	v_mov_b32_e32 v77, v62
	v_mov_b32_e32 v62, v79
	s_waitcnt lgkmcnt(14)
	v_pk_fma_f32 v[98:99], v[124:125], v[154:155], v[98:99] op_sel_hi:[1,0,1] neg_lo:[0,0,1] neg_hi:[0,0,1]
	v_pk_fma_f32 v[48:49], v[48:49], v[150:151], v[100:101] op_sel_hi:[1,0,1] neg_lo:[0,0,1] neg_hi:[0,0,1]
	s_waitcnt lgkmcnt(6)
	v_pk_fma_f32 v[56:57], v[56:57], v[134:135], v[176:177] op_sel_hi:[1,0,1] neg_lo:[0,0,1] neg_hi:[0,0,1]
	s_waitcnt lgkmcnt(5)
	v_pk_fma_f32 v[72:73], v[72:73], v[130:131], v[178:179] op_sel_hi:[1,0,1] neg_lo:[0,0,1] neg_hi:[0,0,1]
	s_waitcnt lgkmcnt(4)
	v_pk_fma_f32 v[58:59], v[58:59], v[128:129], v[180:181] op_sel_hi:[1,0,1] neg_lo:[0,0,1] neg_hi:[0,0,1]
	s_waitcnt lgkmcnt(3)
	v_pk_fma_f32 v[74:75], v[74:75], v[122:123], v[182:183] op_sel_hi:[1,0,1] neg_lo:[0,0,1] neg_hi:[0,0,1]
	s_waitcnt lgkmcnt(2)
	v_pk_fma_f32 v[60:61], v[60:61], v[120:121], v[184:185] op_sel_hi:[1,0,1] neg_lo:[0,0,1] neg_hi:[0,0,1]
	s_waitcnt lgkmcnt(1)
	v_pk_fma_f32 v[76:77], v[76:77], v[112:113], v[186:187] op_sel_hi:[1,0,1] neg_lo:[0,0,1] neg_hi:[0,0,1]
	s_waitcnt lgkmcnt(0)
	v_pk_fma_f32 v[62:63], v[62:63], v[114:115], v[188:189] op_sel_hi:[1,0,1] neg_lo:[0,0,1] neg_hi:[0,0,1]
	ds_read2_b32 v[78:79], v166 offset0:64 offset1:96
	ds_read2_b32 v[176:177], v166 offset0:192 offset1:224
	ds_read2_b32 v[178:179], v168 offset0:64 offset1:96
	ds_read2_b32 v[180:181], v168 offset0:192 offset1:224
	ds_read2_b32 v[182:183], v169 offset0:64 offset1:96
	ds_read2_b32 v[184:185], v169 offset0:192 offset1:224
	ds_read2_b32 v[186:187], v170 offset0:64 offset1:96
	ds_read2_b32 v[188:189], v170 offset0:192 offset1:224
	ds_read2_b32 v[190:191], v171 offset0:64 offset1:96
	ds_read2_b32 v[192:193], v171 offset0:192 offset1:224
	ds_read2_b32 v[194:195], v172 offset0:64 offset1:96
	ds_read2_b32 v[196:197], v172 offset0:192 offset1:224
	ds_read2_b32 v[198:199], v173 offset0:64 offset1:96
	ds_read2_b32 v[200:201], v173 offset0:192 offset1:224
	ds_read2_b32 v[202:203], v174 offset0:64 offset1:96
	ds_read2_b32 v[204:205], v174 offset0:192 offset1:224
	v_mov_b32_e32 v206, v32
	v_mov_b32_e32 v207, v16
	v_mov_b32_e32 v16, v33
	v_pk_mul_f32 v[162:163], v[98:99], v[98:99]
	v_pk_mul_f32 v[164:165], v[48:49], v[48:49]
	s_waitcnt lgkmcnt(14)
	v_pk_fma_f32 v[78:79], v[206:207], v[154:155], v[78:79] op_sel_hi:[1,0,1] neg_lo:[0,0,1] neg_hi:[0,0,1]
	v_pk_fma_f32 v[16:17], v[16:17], v[150:151], v[176:177] op_sel_hi:[1,0,1] neg_lo:[0,0,1] neg_hi:[0,0,1]
	v_mov_b32_e32 v32, v34
	v_mov_b32_e32 v33, v18
	v_mov_b32_e32 v18, v35
	v_mov_b32_e32 v34, v36
	v_mov_b32_e32 v35, v20
	v_mov_b32_e32 v20, v37
	v_mov_b32_e32 v36, v38
	v_mov_b32_e32 v37, v22
	v_pk_mul_f32 v[206:207], v[78:79], v[78:79]
	v_pk_mul_f32 v[176:177], v[16:17], v[16:17]
	s_waitcnt lgkmcnt(9)
	v_pk_fma_f32 v[36:37], v[36:37], v[136:137], v[186:187] op_sel_hi:[1,0,1] neg_lo:[0,0,1] neg_hi:[0,0,1]
	v_mov_b32_e32 v186, v164
	v_mov_b32_e32 v187, v162
	v_mov_b32_e32 v162, v165
	v_pk_add_f32 v[162:163], v[186:187], v[162:163]
	v_mov_b32_e32 v164, v176
	v_mov_b32_e32 v165, v206
	v_pk_add_f32 v[162:163], v[162:163], v[164:165]
	v_mov_b32_e32 v206, v177
	v_xor_b32_e32 v175, 4, v115
	v_pk_add_f32 v[162:163], v[162:163], v[206:207]
	ds_bpermute_b32 v165, v175, v163
	ds_bpermute_b32 v164, v175, v162
	v_pk_fma_f32 v[64:65], v[64:65], v[148:149], v[102:103] op_sel_hi:[1,0,1] neg_lo:[0,0,1] neg_hi:[0,0,1]
	v_pk_fma_f32 v[32:33], v[32:33], v[148:149], v[178:179] op_sel_hi:[1,0,1] neg_lo:[0,0,1] neg_hi:[0,0,1]
	v_xor_b32_e32 v148, 8, v115
	v_xor_b32_e32 v150, 16, v115
	s_waitcnt lgkmcnt(0)
	v_pk_add_f32 v[162:163], v[162:163], v[164:165]
	ds_bpermute_b32 v165, v148, v163
	ds_bpermute_b32 v164, v148, v162
	v_pk_fma_f32 v[50:51], v[50:51], v[146:147], v[104:105] op_sel_hi:[1,0,1] neg_lo:[0,0,1] neg_hi:[0,0,1]
	v_pk_mul_f32 v[158:159], v[64:65], v[64:65]
	v_pk_mul_f32 v[160:161], v[50:51], v[50:51]
	v_pk_fma_f32 v[18:19], v[18:19], v[146:147], v[180:181] op_sel_hi:[1,0,1] neg_lo:[0,0,1] neg_hi:[0,0,1]
	s_waitcnt lgkmcnt(0)
	v_pk_add_f32 v[162:163], v[162:163], v[164:165]
	ds_bpermute_b32 v165, v150, v163
	ds_bpermute_b32 v164, v150, v162
	v_mov_b32_e32 v22, v39
	v_mov_b32_e32 v39, v24
	v_mov_b32_e32 v24, v41
	v_mov_b32_e32 v41, v26
	v_mov_b32_e32 v26, v43
	v_mov_b32_e32 v43, v28
	v_mov_b32_e32 v28, v45
	v_mov_b32_e32 v45, v30
	v_mov_b32_e32 v30, v47
	v_pk_mul_f32 v[178:179], v[32:33], v[32:33]
	v_pk_mul_f32 v[180:181], v[18:19], v[18:19]
	v_xor_b32_e32 v154, 32, v115
	s_waitcnt lgkmcnt(0)
	v_pk_add_f32 v[164:165], v[162:163], v[164:165]
	v_pk_fma_f32 v[30:31], v[30:31], v[114:115], v[204:205] op_sel_hi:[1,0,1] neg_lo:[0,0,1] neg_hi:[0,0,1]
	v_xor_b32_e32 v162, 64, v115
	v_mov_b32_e32 v114, v160
	v_mov_b32_e32 v115, v158
	v_mov_b32_e32 v158, v161
	v_pk_add_f32 v[114:115], v[114:115], v[158:159]
	v_mov_b32_e32 v158, v180
	v_mov_b32_e32 v159, v178
	v_pk_add_f32 v[114:115], v[114:115], v[158:159]
	v_mov_b32_e32 v178, v181
	v_pk_add_f32 v[158:159], v[114:115], v[178:179]
	ds_bpermute_b32 v161, v175, v159
	ds_bpermute_b32 v160, v175, v158
	ds_bpermute_b32 v177, v154, v165
	ds_bpermute_b32 v176, v154, v164
	v_mov_b32_e32 v38, v40
	v_mov_b32_e32 v40, v42
	s_waitcnt lgkmcnt(2)
	v_pk_add_f32 v[158:159], v[158:159], v[160:161]
	ds_bpermute_b32 v161, v148, v159
	ds_bpermute_b32 v160, v148, v158
	v_mov_b32_e32 v42, v44
	v_mov_b32_e32 v44, v46
	s_waitcnt lgkmcnt(2)
	v_pk_add_f32 v[46:47], v[164:165], v[176:177]
	ds_bpermute_b32 v165, v162, v47
	ds_bpermute_b32 v164, v162, v46
	s_waitcnt lgkmcnt(2)
	v_pk_add_f32 v[158:159], v[158:159], v[160:161]
	s_mov_b32 s4, 0x358637bd
	ds_bpermute_b32 v161, v150, v159
	ds_bpermute_b32 v160, v150, v158
	s_waitcnt lgkmcnt(2)
	v_pk_add_f32 v[164:165], v[46:47], v[164:165]
	v_mov_b64_e32 v[46:47], s[4:5]
	v_pk_fma_f32 v[66:67], v[66:67], v[140:141], v[106:107] op_sel_hi:[1,0,1] neg_lo:[0,0,1] neg_hi:[0,0,1]
	v_pk_fma_f32 v[52:53], v[52:53], v[142:143], v[108:109] op_sel_hi:[1,0,1] neg_lo:[0,0,1] neg_hi:[0,0,1]
	v_pk_fma_f32 v[164:165], v[164:165], s[50:51], v[46:47] op_sel_hi:[1,0,0]
	v_pk_mul_f32 v[152:153], v[66:67], v[66:67]
	v_pk_mul_f32 v[156:157], v[52:53], v[52:53]
	v_pk_fma_f32 v[70:71], v[70:71], v[138:139], v[118:119] op_sel_hi:[1,0,1] neg_lo:[0,0,1] neg_hi:[0,0,1]
	v_pk_fma_f32 v[34:35], v[34:35], v[140:141], v[182:183] op_sel_hi:[1,0,1] neg_lo:[0,0,1] neg_hi:[0,0,1]
	v_pk_fma_f32 v[20:21], v[20:21], v[142:143], v[184:185] op_sel_hi:[1,0,1] neg_lo:[0,0,1] neg_hi:[0,0,1]
	v_pk_fma_f32 v[38:39], v[38:39], v[138:139], v[190:191] op_sel_hi:[1,0,1] neg_lo:[0,0,1] neg_hi:[0,0,1]
	v_mul_f32_e32 v138, 0x4b800000, v165
	v_cmp_gt_f32_e32 vcc, s94, v165
	v_mul_f32_e32 v142, 0x4b800000, v164
	v_cmp_gt_f32_e64 s[4:5], s94, v164
	v_pk_mul_f32 v[182:183], v[34:35], v[34:35]
	v_pk_mul_f32 v[184:185], v[20:21], v[20:21]
	v_cndmask_b32_e32 v138, v165, v138, vcc
	v_cndmask_b32_e64 v142, v164, v142, s[4:5]
	v_mov_b32_e32 v164, v156
	v_mov_b32_e32 v165, v152
	v_mov_b32_e32 v152, v157
	s_waitcnt lgkmcnt(0)
	v_pk_add_f32 v[158:159], v[158:159], v[160:161]
	v_pk_add_f32 v[152:153], v[164:165], v[152:153]
	v_mov_b32_e32 v156, v184
	v_mov_b32_e32 v157, v182
	ds_bpermute_b32 v161, v154, v159
	ds_bpermute_b32 v160, v154, v158
	v_pk_add_f32 v[152:153], v[152:153], v[156:157]
	v_mov_b32_e32 v182, v185
	v_pk_add_f32 v[152:153], v[152:153], v[182:183]
	ds_bpermute_b32 v157, v175, v153
	ds_bpermute_b32 v156, v175, v152
	s_waitcnt lgkmcnt(2)
	v_pk_add_f32 v[158:159], v[158:159], v[160:161]
	ds_bpermute_b32 v161, v162, v159
	ds_bpermute_b32 v160, v162, v158
	v_rsq_f32_e32 v138, v138
	s_waitcnt lgkmcnt(2)
	v_pk_add_f32 v[152:153], v[152:153], v[156:157]
	v_rsq_f32_e32 v142, v142
	ds_bpermute_b32 v157, v148, v153
	ds_bpermute_b32 v156, v148, v152
	v_mul_f32_e32 v146, 0x45800000, v138
	s_waitcnt lgkmcnt(2)
	v_pk_add_f32 v[158:159], v[158:159], v[160:161]
	v_cndmask_b32_e32 v138, v138, v146, vcc
	v_mul_f32_e32 v146, 0x45800000, v142
	v_pk_fma_f32 v[158:159], v[158:159], s[50:51], v[46:47] op_sel_hi:[1,0,0]
	v_cndmask_b32_e64 v142, v142, v146, s[4:5]
	v_mul_f32_e32 v146, 0x4b800000, v159
	v_cmp_gt_f32_e32 vcc, s94, v159
	s_waitcnt lgkmcnt(0)
	v_pk_add_f32 v[152:153], v[152:153], v[156:157]
	ds_bpermute_b32 v157, v150, v153
	v_cndmask_b32_e32 v146, v159, v146, vcc
	ds_bpermute_b32 v156, v150, v152
	v_rsq_f32_e32 v146, v146
	v_mul_f32_e32 v159, 0x4b800000, v158
	v_cmp_gt_f32_e64 s[4:5], s94, v158
	v_pk_fma_f32 v[68:69], v[68:69], v[136:137], v[110:111] op_sel_hi:[1,0,1] neg_lo:[0,0,1] neg_hi:[0,0,1]
	v_pk_fma_f32 v[54:55], v[54:55], v[132:133], v[116:117] op_sel_hi:[1,0,1] neg_lo:[0,0,1] neg_hi:[0,0,1]
	v_cndmask_b32_e64 v158, v158, v159, s[4:5]
	v_pk_mul_f32 v[124:125], v[68:69], v[68:69]
	v_pk_mul_f32 v[126:127], v[54:55], v[54:55]
	v_pk_fma_f32 v[22:23], v[22:23], v[132:133], v[188:189] op_sel_hi:[1,0,1] neg_lo:[0,0,1] neg_hi:[0,0,1]
	v_rsq_f32_e32 v160, v158
	s_waitcnt lgkmcnt(0)
	v_pk_add_f32 v[152:153], v[152:153], v[156:157]
	v_mul_f32_e32 v158, 0x45800000, v146
	v_pk_mul_f32 v[136:137], v[36:37], v[36:37]
	v_pk_mul_f32 v[140:141], v[22:23], v[22:23]
	ds_bpermute_b32 v157, v154, v153
	ds_bpermute_b32 v156, v154, v152
	v_cndmask_b32_e32 v146, v146, v158, vcc
	v_mov_b32_e32 v158, v126
	v_mov_b32_e32 v159, v124
	v_mov_b32_e32 v124, v127
	v_pk_add_f32 v[124:125], v[158:159], v[124:125]
	v_mov_b32_e32 v126, v140
	v_mov_b32_e32 v127, v136
	v_pk_add_f32 v[124:125], v[124:125], v[126:127]
	v_mov_b32_e32 v136, v141
	v_pk_add_f32 v[126:127], v[124:125], v[136:137]
	ds_bpermute_b32 v137, v175, v127
	ds_bpermute_b32 v136, v175, v126
	s_waitcnt lgkmcnt(2)
	v_pk_add_f32 v[152:153], v[152:153], v[156:157]
	ds_bpermute_b32 v157, v162, v153
	ds_bpermute_b32 v156, v162, v152
	v_mul_f32_e32 v161, 0x45800000, v160
	s_waitcnt lgkmcnt(2)
	v_pk_add_f32 v[126:127], v[126:127], v[136:137]
	ds_bpermute_b32 v137, v148, v127
	ds_bpermute_b32 v136, v148, v126
	s_waitcnt lgkmcnt(2)
	v_pk_add_f32 v[140:141], v[152:153], v[156:157]
	v_cndmask_b32_e64 v124, v160, v161, s[4:5]
	v_pk_fma_f32 v[140:141], v[140:141], s[50:51], v[46:47] op_sel_hi:[1,0,0]
	v_pk_mul_f32 v[116:117], v[70:71], v[70:71]
	v_mul_f32_e32 v125, 0x4b800000, v141
	v_cmp_gt_f32_e32 vcc, s94, v141
	s_waitcnt lgkmcnt(0)
	v_pk_add_f32 v[126:127], v[126:127], v[136:137]
	ds_bpermute_b32 v137, v150, v127
	v_cndmask_b32_e32 v125, v141, v125, vcc
	v_rsq_f32_e32 v125, v125
	ds_bpermute_b32 v136, v150, v126
	v_mul_f32_e32 v141, 0x4b800000, v140
	v_cmp_gt_f32_e64 s[4:5], s94, v140
	v_pk_mul_f32 v[118:119], v[56:57], v[56:57]
	v_pk_fma_f32 v[24:25], v[24:25], v[134:135], v[192:193] op_sel_hi:[1,0,1] neg_lo:[0,0,1] neg_hi:[0,0,1]
	v_cndmask_b32_e64 v140, v140, v141, s[4:5]
	v_rsq_f32_e32 v152, v140
	v_mul_f32_e32 v140, 0x45800000, v125
	v_pk_mul_f32 v[132:133], v[38:39], v[38:39]
	v_pk_mul_f32 v[134:135], v[24:25], v[24:25]
	v_cndmask_b32_e32 v125, v125, v140, vcc
	v_mov_b32_e32 v140, v118
	v_mov_b32_e32 v141, v116
	v_mov_b32_e32 v116, v119
	s_waitcnt lgkmcnt(0)
	v_pk_add_f32 v[126:127], v[126:127], v[136:137]
	v_pk_add_f32 v[116:117], v[140:141], v[116:117]
	v_mov_b32_e32 v118, v134
	v_mov_b32_e32 v119, v132
	ds_bpermute_b32 v137, v154, v127
	ds_bpermute_b32 v136, v154, v126
	v_pk_add_f32 v[116:117], v[116:117], v[118:119]
	v_mov_b32_e32 v132, v135
	v_pk_add_f32 v[118:119], v[116:117], v[132:133]
	ds_bpermute_b32 v133, v175, v119
	ds_bpermute_b32 v132, v175, v118
	s_waitcnt lgkmcnt(2)
	v_pk_add_f32 v[126:127], v[126:127], v[136:137]
	ds_bpermute_b32 v137, v162, v127
	ds_bpermute_b32 v136, v162, v126
	v_pk_mul_f32 v[108:109], v[72:73], v[72:73]
	s_waitcnt lgkmcnt(2)
	v_pk_add_f32 v[118:119], v[118:119], v[132:133]
	ds_bpermute_b32 v133, v148, v119
	ds_bpermute_b32 v132, v148, v118
	s_waitcnt lgkmcnt(2)
	v_pk_add_f32 v[126:127], v[126:127], v[136:137]
	v_pk_mul_f32 v[110:111], v[58:59], v[58:59]
	v_pk_fma_f32 v[126:127], v[126:127], s[50:51], v[46:47] op_sel_hi:[1,0,0]
	v_pk_fma_f32 v[40:41], v[40:41], v[130:131], v[194:195] op_sel_hi:[1,0,1] neg_lo:[0,0,1] neg_hi:[0,0,1]
	v_mul_f32_e32 v117, 0x4b800000, v127
	v_cmp_gt_f32_e32 vcc, s94, v127
	s_waitcnt lgkmcnt(0)
	v_pk_add_f32 v[118:119], v[118:119], v[132:133]
	ds_bpermute_b32 v133, v150, v119
	v_cndmask_b32_e32 v117, v127, v117, vcc
	ds_bpermute_b32 v132, v150, v118
	v_rsq_f32_e32 v117, v117
	v_pk_fma_f32 v[26:27], v[26:27], v[128:129], v[196:197] op_sel_hi:[1,0,1] neg_lo:[0,0,1] neg_hi:[0,0,1]
	v_pk_mul_f32 v[130:131], v[40:41], v[40:41]
	v_pk_mul_f32 v[128:129], v[26:27], v[26:27]
	s_waitcnt lgkmcnt(0)
	v_pk_add_f32 v[118:119], v[118:119], v[132:133]
	v_mul_f32_e32 v132, 0x45800000, v117
	v_cndmask_b32_e32 v117, v117, v132, vcc
	v_mov_b32_e32 v132, v110
	v_mov_b32_e32 v133, v108
	v_mov_b32_e32 v108, v111
	v_pk_add_f32 v[108:109], v[132:133], v[108:109]
	v_mov_b32_e32 v110, v128
	v_mov_b32_e32 v111, v130
	v_pk_add_f32 v[108:109], v[108:109], v[110:111]
	v_mov_b32_e32 v130, v129
	v_pk_add_f32 v[108:109], v[108:109], v[130:131]
	ds_bpermute_b32 v111, v175, v109
	ds_bpermute_b32 v110, v175, v108
	v_mul_f32_e32 v153, 0x45800000, v152
	v_cndmask_b32_e64 v116, v152, v153, s[4:5]
	v_mul_f32_e32 v127, 0x4b800000, v126
	v_cmp_gt_f32_e64 s[4:5], s94, v126
	s_waitcnt lgkmcnt(0)
	v_pk_add_f32 v[108:109], v[108:109], v[110:111]
	ds_bpermute_b32 v111, v148, v109
	v_cndmask_b32_e64 v126, v126, v127, s[4:5]
	v_rsq_f32_e32 v134, v126
	ds_bpermute_b32 v127, v154, v119
	ds_bpermute_b32 v126, v154, v118
	ds_bpermute_b32 v110, v148, v108
	v_mul_f32_e32 v135, 0x45800000, v134
	v_cndmask_b32_e64 v128, v134, v135, s[4:5]
	v_pk_mul_f32 v[104:105], v[74:75], v[74:75]
	s_waitcnt lgkmcnt(1)
	v_pk_add_f32 v[118:119], v[118:119], v[126:127]
	s_waitcnt lgkmcnt(0)
	v_pk_add_f32 v[108:109], v[108:109], v[110:111]
	ds_bpermute_b32 v127, v162, v119
	ds_bpermute_b32 v126, v162, v118
	ds_bpermute_b32 v111, v150, v109
	ds_bpermute_b32 v110, v150, v108
	v_pk_mul_f32 v[106:107], v[60:61], v[60:61]
	v_pk_fma_f32 v[42:43], v[42:43], v[122:123], v[198:199] op_sel_hi:[1,0,1] neg_lo:[0,0,1] neg_hi:[0,0,1]
	s_waitcnt lgkmcnt(2)
	v_pk_add_f32 v[118:119], v[118:119], v[126:127]
	v_pk_fma_f32 v[28:29], v[28:29], v[120:121], v[200:201] op_sel_hi:[1,0,1] neg_lo:[0,0,1] neg_hi:[0,0,1]
	s_waitcnt lgkmcnt(0)
	v_pk_add_f32 v[108:109], v[108:109], v[110:111]
	v_pk_fma_f32 v[118:119], v[118:119], s[50:51], v[46:47] op_sel_hi:[1,0,0]
	ds_bpermute_b32 v111, v154, v109
	ds_bpermute_b32 v110, v154, v108
	v_mul_f32_e32 v126, 0x4b800000, v119
	v_cmp_gt_f32_e32 vcc, s94, v119
	v_cmp_gt_f32_e64 s[4:5], s94, v118
	v_pk_mul_f32 v[122:123], v[42:43], v[42:43]
	v_cndmask_b32_e32 v119, v119, v126, vcc
	v_rsq_f32_e32 v119, v119
	v_mul_f32_e32 v126, 0x4b800000, v118
	s_waitcnt lgkmcnt(0)
	v_pk_add_f32 v[108:109], v[108:109], v[110:111]
	v_cndmask_b32_e64 v118, v118, v126, s[4:5]
	ds_bpermute_b32 v111, v162, v109
	ds_bpermute_b32 v110, v162, v108
	v_rsq_f32_e32 v126, v118
	v_mul_f32_e32 v118, 0x45800000, v119
	v_cndmask_b32_e32 v118, v119, v118, vcc
	v_pk_mul_f32 v[120:121], v[28:29], v[28:29]
	v_mul_f32_e32 v127, 0x3f4ccccd, v118
	v_mov_b32_e32 v118, v106
	v_mov_b32_e32 v119, v104
	v_mov_b32_e32 v104, v107
	v_pk_add_f32 v[104:105], v[118:119], v[104:105]
	v_mov_b32_e32 v106, v120
	v_mov_b32_e32 v107, v122
	v_pk_add_f32 v[104:105], v[104:105], v[106:107]
	v_mov_b32_e32 v122, v121
	s_waitcnt lgkmcnt(0)
	v_pk_add_f32 v[108:109], v[108:109], v[110:111]
	v_pk_add_f32 v[104:105], v[104:105], v[122:123]
	v_pk_fma_f32 v[108:109], v[108:109], s[50:51], v[46:47] op_sel_hi:[1,0,0]
	ds_bpermute_b32 v107, v175, v105
	ds_bpermute_b32 v106, v175, v104
	v_mul_f32_e32 v110, 0x4b800000, v109
	v_cmp_gt_f32_e32 vcc, s94, v109
	v_mul_f32_e32 v129, 0x45800000, v126
	v_cndmask_b32_e64 v118, v126, v129, s[4:5]
	v_cndmask_b32_e32 v109, v109, v110, vcc
	v_rsq_f32_e32 v109, v109
	s_waitcnt lgkmcnt(0)
	v_pk_add_f32 v[104:105], v[104:105], v[106:107]
	ds_bpermute_b32 v107, v148, v105
	ds_bpermute_b32 v106, v148, v104
	v_mul_f32_e32 v111, 0x3f4ccccd, v118
	v_mul_f32_e32 v118, 0x45800000, v109
	v_cndmask_b32_e32 v109, v109, v118, vcc
	v_mul_f32_e32 v118, 0x3f4ccccd, v109
	v_mul_f32_e32 v109, 0x4b800000, v108
	v_cmp_gt_f32_e32 vcc, s94, v108
	v_pk_mul_f32 v[100:101], v[76:77], v[76:77]
	v_pk_mul_f32 v[102:103], v[62:63], v[62:63]
	v_pk_fma_f32 v[44:45], v[44:45], v[112:113], v[202:203] op_sel_hi:[1,0,1] neg_lo:[0,0,1] neg_hi:[0,0,1]
	v_cndmask_b32_e32 v108, v108, v109, vcc
	v_pk_mul_f32 v[112:113], v[44:45], v[44:45]
	v_pk_mul_f32 v[114:115], v[30:31], v[30:31]
	v_rsq_f32_e32 v119, v108
	v_mov_b32_e32 v108, v102
	v_mov_b32_e32 v109, v100
	v_mov_b32_e32 v100, v103
	s_waitcnt lgkmcnt(0)
	v_pk_add_f32 v[104:105], v[104:105], v[106:107]
	v_pk_add_f32 v[100:101], v[108:109], v[100:101]
	v_mov_b32_e32 v102, v114
	v_mov_b32_e32 v103, v112
	ds_bpermute_b32 v107, v150, v105
	ds_bpermute_b32 v106, v150, v104
	v_pk_add_f32 v[100:101], v[100:101], v[102:103]
	v_mov_b32_e32 v112, v115
	v_pk_add_f32 v[100:101], v[100:101], v[112:113]
	ds_bpermute_b32 v103, v175, v101
	ds_bpermute_b32 v102, v175, v100
	s_waitcnt lgkmcnt(2)
	v_pk_add_f32 v[104:105], v[104:105], v[106:107]
	ds_bpermute_b32 v107, v154, v105
	ds_bpermute_b32 v106, v154, v104
	v_mul_f32_e32 v108, 0x45800000, v119
	s_waitcnt lgkmcnt(2)
	v_pk_add_f32 v[100:101], v[100:101], v[102:103]
	ds_bpermute_b32 v103, v148, v101
	ds_bpermute_b32 v102, v148, v100
	s_waitcnt lgkmcnt(2)
	v_pk_add_f32 v[104:105], v[104:105], v[106:107]
	ds_bpermute_b32 v107, v162, v105
	ds_bpermute_b32 v106, v162, v104
	global_load_dword v110, v167, s[8:9]
	s_waitcnt lgkmcnt(2)
	v_pk_add_f32 v[100:101], v[100:101], v[102:103]
	ds_bpermute_b32 v103, v150, v101
	ds_bpermute_b32 v102, v150, v100
	s_waitcnt lgkmcnt(2)
	v_pk_add_f32 v[104:105], v[104:105], v[106:107]
	global_load_dword v106, v167, s[8:9] offset:128
	v_pk_fma_f32 v[104:105], v[104:105], s[50:51], v[46:47] op_sel_hi:[1,0,0]
	v_mul_f32_e32 v142, 0x3f4ccccd, v142
	v_mul_f32_e32 v107, 0x4b800000, v105
	v_cmp_gt_f32_e64 s[4:5], s94, v105
	s_waitcnt lgkmcnt(0)
	v_pk_add_f32 v[100:101], v[100:101], v[102:103]
	ds_bpermute_b32 v103, v154, v101
	v_cndmask_b32_e64 v105, v105, v107, s[4:5]
	ds_bpermute_b32 v102, v154, v100
	v_rsq_f32_e32 v105, v105
	v_cndmask_b32_e32 v107, v119, v108, vcc
	v_cmp_gt_f32_e32 vcc, s94, v104
	v_mul_f32_e32 v48, v48, v142
	v_mul_f32_e32 v108, 0x45800000, v105
	s_waitcnt lgkmcnt(0)
	v_pk_add_f32 v[100:101], v[100:101], v[102:103]
	v_cndmask_b32_e64 v105, v105, v108, s[4:5]
	v_mul_f32_e32 v108, 0x4b800000, v104
	ds_bpermute_b32 v103, v162, v101
	ds_bpermute_b32 v102, v162, v100
	v_cndmask_b32_e32 v104, v104, v108, vcc
	v_rsq_f32_e32 v104, v104
	v_mul_f32_e32 v49, v49, v142
	v_mul_f32_e32 v146, 0x3f4ccccd, v146
	s_waitcnt lgkmcnt(0)
	v_pk_add_f32 v[100:101], v[100:101], v[102:103]
	v_mul_f32_e32 v108, 0x45800000, v104
	v_pk_fma_f32 v[46:47], v[100:101], s[50:51], v[46:47] op_sel_hi:[1,0,0]
	v_cndmask_b32_e32 v104, v104, v108, vcc
	v_mul_f32_e32 v100, 0x4b800000, v47
	v_cmp_gt_f32_e32 vcc, s94, v47
	v_cmp_gt_f32_e64 s[4:5], s94, v46
	v_mul_f32_e32 v64, v64, v146
	v_cndmask_b32_e32 v47, v47, v100, vcc
	v_mul_f32_e32 v100, 0x4b800000, v46
	v_rsq_f32_e32 v47, v47
	v_cndmask_b32_e64 v46, v46, v100, s[4:5]
	v_rsq_f32_e32 v46, v46
	v_mul_f32_e32 v16, v16, v142
	v_mul_f32_e32 v100, 0x45800000, v47
	v_cndmask_b32_e32 v47, v47, v100, vcc
	v_mul_f32_e32 v100, 0x45800000, v46
	v_cndmask_b32_e64 v46, v46, v100, s[4:5]
	global_load_dword v100, v167, s[8:9] offset:256
	global_load_dword v101, v167, s[8:9] offset:384
	v_mul_f32_e32 v17, v17, v142
	v_mul_f32_e32 v124, 0x3f4ccccd, v124
	v_mul_f32_e32 v50, v50, v124
	v_mul_f32_e32 v32, v32, v146
	v_mul_f32_e32 v125, 0x3f4ccccd, v125
	v_mul_f32_e32 v66, v66, v125
	v_mul_f32_e32 v18, v18, v124
	v_mul_f32_e32 v116, 0x3f4ccccd, v116
	v_mul_f32_e32 v52, v52, v116
	v_mul_f32_e32 v34, v34, v125
	v_mul_f32_e32 v117, 0x3f4ccccd, v117
	v_mul_f32_e32 v68, v68, v117
	v_mul_f32_e32 v20, v20, v116
	v_mul_f32_e32 v128, 0x3f4ccccd, v128
	v_mul_f32_e32 v54, v54, v128
	v_mul_f32_e32 v36, v36, v117
	v_mul_f32_e32 v70, v70, v127
	v_mul_f32_e32 v22, v22, v128
	v_mul_f32_e32 v56, v56, v111
	v_mul_f32_e32 v38, v38, v127
	v_mul_f32_e32 v72, v72, v118
	v_mul_f32_e32 v24, v24, v111
	v_mul_f32_e32 v107, 0x3f4ccccd, v107
	v_mul_f32_e32 v58, v58, v107
	v_mul_f32_e32 v40, v40, v118
	v_mul_f32_e32 v105, 0x3f4ccccd, v105
	v_mul_f32_e32 v74, v74, v105
	v_mul_f32_e32 v26, v26, v107
	v_mul_f32_e32 v104, 0x3f4ccccd, v104
	v_mul_f32_e32 v60, v60, v104
	v_mul_f32_e32 v42, v42, v105
	v_mul_f32_e32 v47, 0x3f4ccccd, v47
	v_mul_f32_e32 v76, v76, v47
	s_waitcnt vmcnt(3)
	v_mul_f32_e32 v48, v48, v110
	v_mul_f32_e32 v64, v64, v110
	v_mul_f32_e32 v50, v50, v110
	v_mul_f32_e32 v66, v66, v110
	v_mul_f32_e32 v52, v52, v110
	s_waitcnt vmcnt(2)
	v_mul_f32_e32 v49, v49, v106
	ds_write2_b32 v166, v48, v49 offset0:128 offset1:160
	v_mul_f32_e32 v48, v65, v146
	v_mul_f32_e32 v48, v48, v106
	ds_write2_b32 v168, v64, v48 offset1:32
	v_mul_f32_e32 v48, v51, v124
	v_mul_f32_e32 v48, v48, v106
	ds_write2_b32 v168, v50, v48 offset0:128 offset1:160
	v_mul_f32_e32 v48, v67, v125
	v_mul_f32_e32 v48, v48, v106
	ds_write2_b32 v169, v66, v48 offset1:32
	v_mul_f32_e32 v48, v53, v116
	v_mul_f32_e32 v48, v48, v106
	ds_write2_b32 v169, v52, v48 offset0:128 offset1:160
	v_mul_f32_e32 v48, v69, v117
	v_mul_f32_e32 v68, v68, v110
	v_mul_f32_e32 v48, v48, v106
	ds_write2_b32 v170, v68, v48 offset1:32
	v_mul_f32_e32 v48, v55, v128
	v_mul_f32_e32 v54, v54, v110
	v_mul_f32_e32 v48, v48, v106
	ds_write2_b32 v170, v54, v48 offset0:128 offset1:160
	v_mul_f32_e32 v48, v71, v127
	v_mul_f32_e32 v70, v70, v110
	v_mul_f32_e32 v48, v48, v106
	ds_write2_b32 v171, v70, v48 offset1:32
	v_mul_f32_e32 v48, v57, v111
	v_mul_f32_e32 v56, v56, v110
	v_mul_f32_e32 v48, v48, v106
	ds_write2_b32 v171, v56, v48 offset0:128 offset1:160
	v_mul_f32_e32 v48, v73, v118
	v_mul_f32_e32 v72, v72, v110
	v_mul_f32_e32 v48, v48, v106
	ds_write2_b32 v172, v72, v48 offset1:32
	v_mul_f32_e32 v48, v59, v107
	v_mul_f32_e32 v58, v58, v110
	v_mul_f32_e32 v48, v48, v106
	ds_write2_b32 v172, v58, v48 offset0:128 offset1:160
	v_mul_f32_e32 v48, v75, v105
	v_mul_f32_e32 v74, v74, v110
	s_waitcnt vmcnt(1)
	v_mul_f32_e32 v16, v16, v100
	s_waitcnt vmcnt(0)
	v_mul_f32_e32 v17, v17, v101
	ds_write2_b32 v166, v16, v17 offset0:192 offset1:224
	v_mul_f32_e32 v16, v33, v146
	v_mul_f32_e32 v32, v32, v100
	v_mul_f32_e32 v16, v16, v101
	ds_write2_b32 v168, v32, v16 offset0:64 offset1:96
	v_mul_f32_e32 v16, v19, v124
	v_mul_f32_e32 v18, v18, v100
	v_mul_f32_e32 v16, v16, v101
	ds_write2_b32 v168, v18, v16 offset0:192 offset1:224
	v_mul_f32_e32 v16, v35, v125
	v_mul_f32_e32 v34, v34, v100
	v_mul_f32_e32 v16, v16, v101
	ds_write2_b32 v169, v34, v16 offset0:64 offset1:96
	v_mul_f32_e32 v16, v21, v116
	v_mul_f32_e32 v20, v20, v100
	v_mul_f32_e32 v16, v16, v101
	ds_write2_b32 v169, v20, v16 offset0:192 offset1:224
	v_mul_f32_e32 v16, v37, v117
	v_mul_f32_e32 v36, v36, v100
	v_mul_f32_e32 v16, v16, v101
	ds_write2_b32 v170, v36, v16 offset0:64 offset1:96
	v_mul_f32_e32 v16, v23, v128
	v_mul_f32_e32 v22, v22, v100
	v_mul_f32_e32 v16, v16, v101
	ds_write2_b32 v170, v22, v16 offset0:192 offset1:224
	v_mul_f32_e32 v16, v39, v127
	v_mul_f32_e32 v38, v38, v100
	v_mul_f32_e32 v16, v16, v101
	ds_write2_b32 v171, v38, v16 offset0:64 offset1:96
	v_mul_f32_e32 v16, v25, v111
	v_mul_f32_e32 v24, v24, v100
	v_mul_f32_e32 v16, v16, v101
	ds_write2_b32 v171, v24, v16 offset0:192 offset1:224
	v_mul_f32_e32 v16, v41, v118
	v_mul_f32_e32 v40, v40, v100
	v_mul_f32_e32 v16, v16, v101
	ds_write2_b32 v172, v40, v16 offset0:64 offset1:96
	v_mul_f32_e32 v16, v27, v107
	v_mul_f32_e32 v48, v48, v106
	v_mul_f32_e32 v26, v26, v100
	v_mul_f32_e32 v16, v16, v101
	ds_write2_b32 v173, v74, v48 offset1:32
	v_mul_f32_e32 v48, v61, v104
	ds_write2_b32 v172, v26, v16 offset0:192 offset1:224
	v_mul_f32_e32 v16, v43, v105
	v_mul_f32_e32 v60, v110, v60
	v_mul_f32_e32 v48, v48, v106
	v_mul_f32_e32 v42, v42, v100
	v_mul_f32_e32 v16, v16, v101
	ds_write2_b32 v173, v60, v48 offset0:128 offset1:160
	v_mul_f32_e32 v48, v77, v47
	v_mul_f32_e32 v28, v28, v104
	ds_write2_b32 v173, v42, v16 offset0:64 offset1:96
	v_mul_f32_e32 v16, v29, v104
	v_mul_f32_e32 v46, 0x3f4ccccd, v46
	v_mul_f32_e32 v76, v110, v76
	v_mul_f32_e32 v48, v48, v106
	v_mul_f32_e32 v28, v28, v100
	v_mul_f32_e32 v16, v16, v101
	v_mul_f32_e32 v62, v62, v46
	ds_write2_b32 v174, v76, v48 offset1:32
	v_mul_f32_e32 v48, v63, v46
	v_mul_f32_e32 v44, v44, v47
	ds_write2_b32 v173, v28, v16 offset0:192 offset1:224
	v_mul_f32_e32 v16, v45, v47
	v_mul_f32_e32 v138, 0x3f4ccccd, v138
	v_mul_f32_e32 v62, v110, v62
	v_mul_f32_e32 v48, v48, v106
	v_mul_f32_e32 v44, v44, v100
	v_mul_f32_e32 v16, v16, v101
	v_mul_f32_e32 v98, v98, v138
	v_mul_f32_e32 v99, v99, v138
	ds_write2_b32 v174, v62, v48 offset0:128 offset1:160
	v_mul_f32_e32 v48, v78, v138
	v_mul_f32_e32 v30, v30, v46
	v_mul_f32_e32 v49, v79, v138
	ds_write2_b32 v174, v44, v16 offset0:64 offset1:96
	v_mul_f32_e32 v16, v31, v46
	v_mul_f32_e32 v98, v98, v110
	v_mul_f32_e32 v99, v99, v106
	v_mul_f32_e32 v48, v48, v100
	v_mul_f32_e32 v30, v30, v100
	v_mul_f32_e32 v49, v49, v101
	v_mul_f32_e32 v16, v16, v101
	ds_write2_b32 v166, v98, v99 offset1:32
	ds_write2_b32 v166, v48, v49 offset0:64 offset1:96
	ds_write2_b32 v174, v30, v16 offset0:192 offset1:224
.LBB0_660:
	v_lshl_add_u32 v28, v143, 2, s80
	s_waitcnt vmcnt(4) lgkmcnt(0)
	s_barrier
	v_lshl_add_u32 v20, v139, 9, v28
	ds_read_b128 v[16:19], v20
	ds_read_b128 v[20:23], v20 offset:16
	s_waitcnt vmcnt(3)
	v_lshlrev_b32_e32 v26, 16, v92
	v_and_b32_e32 v27, 0xffff0000, v92
	s_add_u32 s4, s6, s10
	s_waitcnt lgkmcnt(1)
	v_pk_mul_f32 v[16:17], v[16:17], v[26:27]
	v_lshlrev_b32_e32 v26, 16, v93
	v_and_b32_e32 v27, 0xffff0000, v93
	v_pk_mul_f32 v[18:19], v[18:19], v[26:27]
	v_cvt_pk_bf16_f32 v16, v16, v17
	v_cvt_pk_bf16_f32 v17, v18, v19
	v_lshlrev_b32_e32 v18, 16, v94
	v_and_b32_e32 v19, 0xffff0000, v94
	s_waitcnt lgkmcnt(0)
	v_pk_mul_f32 v[18:19], v[20:21], v[18:19]
	v_lshlrev_b32_e32 v20, 16, v95
	v_and_b32_e32 v21, 0xffff0000, v95
	s_addc_u32 s5, s7, 0
	v_pk_mul_f32 v[20:21], v[22:23], v[20:21]
	v_add_u32_e32 v29, 4, v139
	v_lshl_add_u64 v[24:25], s[4:5], 0, v[144:145]
	v_cvt_pk_bf16_f32 v18, v18, v19
	v_cvt_pk_bf16_f32 v19, v20, v21
	v_lshlrev_b64 v[20:21], 11, v[96:97]
	v_lshl_add_u32 v30, v29, 9, v28
	v_lshl_add_u64 v[26:27], v[24:25], 0, v[20:21]
	ds_read_b128 v[20:23], v30
	global_store_dwordx4 v[26:27], v[16:19], off
	ds_read_b128 v[16:19], v30 offset:16
	s_waitcnt vmcnt(3)
	v_lshlrev_b32_e32 v26, 16, v88
	v_and_b32_e32 v27, 0xffff0000, v88
	s_waitcnt lgkmcnt(1)
	v_pk_mul_f32 v[20:21], v[20:21], v[26:27]
	v_lshlrev_b32_e32 v26, 16, v89
	v_and_b32_e32 v27, 0xffff0000, v89
	v_pk_mul_f32 v[22:23], v[22:23], v[26:27]
	v_cvt_pk_bf16_f32 v20, v20, v21
	v_cvt_pk_bf16_f32 v21, v22, v23
	v_lshlrev_b32_e32 v22, 16, v90
	v_and_b32_e32 v23, 0xffff0000, v90
	s_waitcnt lgkmcnt(0)
	v_pk_mul_f32 v[16:17], v[16:17], v[22:23]
	s_mov_b64 s[4:5], 0
	v_cvt_pk_bf16_f32 v22, v16, v17
	v_lshlrev_b32_e32 v16, 16, v91
	v_and_b32_e32 v17, 0xffff0000, v91
	v_pk_mul_f32 v[16:17], v[18:19], v[16:17]
	s_nop 0
	v_cvt_pk_bf16_f32 v23, v16, v17
	v_add_u32_e32 v16, s59, v29
	v_ashrrev_i32_e32 v17, 31, v16
	v_add_u32_e32 v29, 8, v139
	v_lshlrev_b64 v[16:17], 11, v[16:17]
	v_lshl_add_u32 v30, v29, 9, v28
	v_lshl_add_u64 v[26:27], v[24:25], 0, v[16:17]
	ds_read_b128 v[16:19], v30
	global_store_dwordx4 v[26:27], v[20:23], off
	ds_read_b128 v[20:23], v30 offset:16
	s_waitcnt vmcnt(3)
	v_lshlrev_b32_e32 v26, 16, v84
	v_and_b32_e32 v27, 0xffff0000, v84
	s_waitcnt lgkmcnt(1)
	v_pk_mul_f32 v[16:17], v[16:17], v[26:27]
	v_lshlrev_b32_e32 v26, 16, v85
	v_and_b32_e32 v27, 0xffff0000, v85
	v_pk_mul_f32 v[18:19], v[18:19], v[26:27]
	v_cvt_pk_bf16_f32 v16, v16, v17
	v_cvt_pk_bf16_f32 v17, v18, v19
	v_lshlrev_b32_e32 v18, 16, v86
	v_and_b32_e32 v19, 0xffff0000, v86
	s_waitcnt lgkmcnt(0)
	v_pk_mul_f32 v[18:19], v[20:21], v[18:19]
	v_lshlrev_b32_e32 v20, 16, v87
	v_and_b32_e32 v21, 0xffff0000, v87
	v_pk_mul_f32 v[20:21], v[22:23], v[20:21]
	v_cvt_pk_bf16_f32 v18, v18, v19
	v_cvt_pk_bf16_f32 v19, v20, v21
	v_add_u32_e32 v20, s59, v29
	v_ashrrev_i32_e32 v21, 31, v20
	v_add_u32_e32 v29, 12, v139
	v_lshlrev_b64 v[20:21], 11, v[20:21]
	v_lshl_add_u32 v28, v29, 9, v28
	v_lshl_add_u64 v[26:27], v[24:25], 0, v[20:21]
	ds_read_b128 v[20:23], v28
	global_store_dwordx4 v[26:27], v[16:19], off
	ds_read_b128 v[16:19], v28 offset:16
	s_waitcnt vmcnt(3)
	v_lshlrev_b32_e32 v26, 16, v80
	v_and_b32_e32 v27, 0xffff0000, v80
	s_waitcnt lgkmcnt(1)
	v_pk_mul_f32 v[20:21], v[20:21], v[26:27]
	v_lshlrev_b32_e32 v26, 16, v81
	v_and_b32_e32 v27, 0xffff0000, v81
	v_pk_mul_f32 v[22:23], v[22:23], v[26:27]
	v_cvt_pk_bf16_f32 v20, v20, v21
	v_cvt_pk_bf16_f32 v21, v22, v23
	v_lshlrev_b32_e32 v22, 16, v82
	v_and_b32_e32 v23, 0xffff0000, v82
	s_waitcnt lgkmcnt(0)
	v_pk_mul_f32 v[16:17], v[16:17], v[22:23]
	s_nop 0
	v_cvt_pk_bf16_f32 v22, v16, v17
	v_lshlrev_b32_e32 v16, 16, v83
	v_and_b32_e32 v17, 0xffff0000, v83
	v_pk_mul_f32 v[16:17], v[18:19], v[16:17]
	s_nop 0
	v_cvt_pk_bf16_f32 v23, v16, v17
	v_add_u32_e32 v16, s59, v29
	v_ashrrev_i32_e32 v17, 31, v16
	v_lshlrev_b64 v[16:17], 11, v[16:17]
	v_lshl_add_u64 v[16:17], v[24:25], 0, v[16:17]
	global_store_dwordx4 v[16:17], v[20:23], off
